# first-half exps issued speculatively into spare VGPRs, interleaved with the row-max reduction before the threshold branch (originals kept for the rare path); second half as v29
# speedup vs baseline: 1.0047x; 1.0047x over previous
; __device__ __forceinline__ float max3f(float a, float b, float c) { return __builtin_fmaxf(__builtin_fmaxf(a, b), c); }
; __device__ __forceinline__ void rowmax_adjust(f32x16& p0, f32x16& p1, float& m2, f32x16& negm, float& alpha, const bool first) {
;     constexpr float THR2 = THR * 1.4426950408889634f;
;     float pmax = max3f(p0[0], p0[1], p0[2]);
; #pragma unroll
;     for (int r = 3; r < 15; r += 2) pmax = max3f(pmax, p0[r], p0[r + 1]);
;     pmax = max3f(pmax, p0[15], p1[0]);
; #pragma unroll
;     for (int r = 1; r < 15; r += 2) pmax = max3f(pmax, p1[r], p1[r + 1]);
;     pmax = fmaxf(pmax, p1[15]);
;     { auto rr = __builtin_amdgcn_permlane32_swap(__float_as_uint(pmax), __float_as_uint(pmax), false, false);
;       pmax = fmaxf(__uint_as_float(rr[0]), __uint_as_float(rr[1])); }
;     if (!first && __builtin_expect(__all(pmax <= THR2), 1)) { alpha = 1.f; }
; __device__ __forceinline__ float exp_pack(f32x16& p0, f32x16& p1, bf16x8& pa0, bf16x8& pa1, bf16x8& pa2, bf16x8& pa3) {
; #pragma unroll
;     for (int r = 0; r < 16; ++r) p0[r] = __builtin_amdgcn_exp2f(p0[r]);
.Ld1_a_nopv:
	s_waitcnt lgkmcnt(0)
	s_mov_b64 s[0:1], s[72:73]
	s_barrier
	v_max3_f32 v168, v96, v97, v98
	v_exp_f32_e32 v240, v96
	v_max3_f32 v169, v81, v82, v83
	v_exp_f32_e32 v241, v97
	v_max3_f32 v168, v168, v99, v100
	v_exp_f32_e32 v242, v98
	v_max3_f32 v169, v169, v84, v85
	v_exp_f32_e32 v243, v99
	v_max3_f32 v168, v168, v101, v102
	v_exp_f32_e32 v244, v100
	v_max3_f32 v169, v169, v86, v87
	v_exp_f32_e32 v245, v101
	v_max3_f32 v168, v168, v103, v104
	v_exp_f32_e32 v246, v102
	v_max3_f32 v169, v169, v88, v89
	v_exp_f32_e32 v247, v103
	v_max3_f32 v168, v168, v105, v106
	v_exp_f32_e32 v248, v104
	v_max3_f32 v169, v169, v90, v91
	v_exp_f32_e32 v249, v105
	v_max3_f32 v168, v168, v107, v108
	v_exp_f32_e32 v250, v106
	v_max3_f32 v169, v169, v92, v93
	v_exp_f32_e32 v251, v107
	v_max3_f32 v168, v168, v109, v110
	v_exp_f32_e32 v252, v108
	v_max3_f32 v169, v169, v94, v95
	v_exp_f32_e32 v253, v109
	v_max3_f32 v168, v168, v111, v80
	v_exp_f32_e32 v236, v110
	v_max_f32_e32 v168, v168, v169
	v_exp_f32_e32 v237, v111
	v_mov_b32_e32 v169, v168
	s_nop 1
	v_permlane32_swap_b32_e32 v168, v169
	v_max_f32_e32 v168, v168, v169
	v_cmp_ge_f32_e32 vcc, s83, v168
	v_mov_b32_e32 v184, 1.0
	s_cmp_lg_u64 s[0:1], 0
	s_cbranch_scc1 .Lvt0_first
	s_cmp_lg_u64 vcc, exec
	s_cbranch_scc1 .Lvt0_rare
	s_branch .Lsp_de0

; #define SBAR() __builtin_amdgcn_sched_barrier(0)
; #define PK4(P, BASE, OUT) do { u32x4 w = {cvtpk_a(P[BASE + 0], P[BASE + 1]), cvtpk_a(P[BASE + 2], P[BASE + 3]), cvtpk_a(P[BASE + 4], P[BASE + 5]), cvtpk_a(P[BASE + 6], P[BASE + 7])}; \
;     OUT = *reinterpret_cast<bf16x8*>(&w); } while (0)
; #define SWAIT() asm volatile("s_waitcnt vmcnt(3)" ::: "memory")
; __device__ __forceinline__ float exp_pack(f32x16& p0, f32x16& p1, bf16x8& pa0, bf16x8& pa1, bf16x8& pa2, bf16x8& pa3) {
; #pragma unroll
;     for (int r = 0; r < 16; ++r) p0[r] = __builtin_amdgcn_exp2f(p0[r]);
; #pragma unroll
;     for (int r = 0; r < 16; ++r) p1[r] = __builtin_amdgcn_exp2f(p1[r]);
;     SBAR(); asm volatile("s_nop 1" ::: "memory"); SBAR();
;     ...
;     PK4(p0, 0, pa0); PK4(p0, 8, pa1); PK4(p1, 0, pa2); PK4(p1, 8, pa3);
;     ...
;     float ps0 = p0[0], ps1 = p1[0];
; #pragma unroll
;     for (int r = 1; r < 16; ++r) { ps0 += p0[r]; ps1 += p1[r]; }
;     float ps = ps0 + ps1;
;     { auto rr = __builtin_amdgcn_permlane32_swap(__float_as_uint(ps), __float_as_uint(ps), false, false);
;       ps = __uint_as_float(rr[0]) + __uint_as_float(rr[1]); }
;     return ps;
; template <bool MLA>
; __device__ __forceinline__ void attn_core(const bf16_t* __restrict__ Qb, const bf16_t* __restrict__ Kh, const bf16_t* __restrict__ Vh, int seq, char* lds,
;                                           f32x16 (&o)[Cfg<MLA>::NCB], const int wid  , const int g  ) {
;     ...
;         SWAIT(); if (j + 2 < NT) SWRITE(((j + 2) % 3) * SHM_K, ((j + 2) & 3) * SHM_V, SE);
.LBB0_1162:
	v_exp_f32_e32 v240, v96
	v_exp_f32_e32 v241, v97
	v_exp_f32_e32 v242, v98
	v_exp_f32_e32 v243, v99
	v_exp_f32_e32 v244, v100
	v_exp_f32_e32 v245, v101
	v_exp_f32_e32 v246, v102
	v_exp_f32_e32 v247, v103
	v_exp_f32_e32 v248, v104
	v_exp_f32_e32 v249, v105
	v_exp_f32_e32 v250, v106
	v_exp_f32_e32 v251, v107
	v_exp_f32_e32 v252, v108
	v_exp_f32_e32 v253, v109
	v_exp_f32_e32 v236, v110
	v_exp_f32_e32 v237, v111
.Lsp_de0:
	v_exp_f32_e32 v80, v80
	v_cvt_pk_bf16_f32 v180, v240, v241
	v_cvt_pk_bf16_f32 v176, v248, v249
	v_exp_f32_e32 v81, v81
	v_add_f32_e32 v240, v240, v241
	v_exp_f32_e32 v82, v82
	v_add_f32_e32 v248, v248, v249
	v_add_f32_e32 v240, v242, v240
	v_exp_f32_e32 v83, v83
	v_add_f32_e32 v248, v250, v248
	v_exp_f32_e32 v84, v84
	v_cvt_pk_bf16_f32 v181, v242, v243
	v_add_f32_e32 v240, v243, v240
	v_exp_f32_e32 v85, v85
	v_add_f32_e32 v248, v251, v248
	v_exp_f32_e32 v86, v86
	v_cvt_pk_bf16_f32 v177, v250, v251
	v_add_f32_e32 v240, v244, v240
	v_exp_f32_e32 v87, v87
	v_add_f32_e32 v248, v252, v248
	v_exp_f32_e32 v88, v88
	v_cvt_pk_bf16_f32 v182, v244, v245
	v_add_f32_e32 v240, v245, v240
	v_exp_f32_e32 v89, v89
	v_add_f32_e32 v248, v253, v248
	v_exp_f32_e32 v90, v90
	v_cvt_pk_bf16_f32 v178, v252, v253
	v_add_f32_e32 v240, v246, v240
	v_exp_f32_e32 v91, v91
	v_add_f32_e32 v248, v236, v248
	v_exp_f32_e32 v92, v92
	v_cvt_pk_bf16_f32 v183, v246, v247
	v_add_f32_e32 v240, v247, v240
	v_exp_f32_e32 v93, v93
	v_add_f32_e32 v248, v237, v248
	v_exp_f32_e32 v94, v94
	v_cvt_pk_bf16_f32 v179, v236, v237
	v_add_f32_e32 v240, v240, v248
	v_exp_f32_e32 v95, v95
	v_cvt_pk_bf16_f32 v172, v80, v81
	v_cvt_pk_bf16_f32 v168, v88, v89
	v_add_f32_e32 v80, v80, v81
	v_add_f32_e32 v88, v88, v89
	v_add_f32_e32 v80, v82, v80
	v_add_f32_e32 v88, v90, v88
	v_cvt_pk_bf16_f32 v173, v82, v83
	v_add_f32_e32 v80, v83, v80
	v_add_f32_e32 v88, v91, v88
	v_cvt_pk_bf16_f32 v169, v90, v91
	v_add_f32_e32 v80, v84, v80
	v_add_f32_e32 v88, v92, v88
	v_cvt_pk_bf16_f32 v174, v84, v85
	v_add_f32_e32 v80, v85, v80
	v_add_f32_e32 v88, v93, v88
	v_cvt_pk_bf16_f32 v170, v92, v93
	v_add_f32_e32 v80, v86, v80
	v_add_f32_e32 v88, v94, v88
	v_cvt_pk_bf16_f32 v175, v86, v87
	v_add_f32_e32 v80, v87, v80
	v_add_f32_e32 v88, v95, v88
	v_cvt_pk_bf16_f32 v171, v94, v95
	v_add_f32_e32 v80, v80, v88
	v_add_f32_e32 v185, v80, v240
	s_waitcnt vmcnt(3)
	s_cmpk_gt_u32 s95, 0x81
	s_cbranch_scc1 .LBB0_1164
	s_add_i32 s0, s51, 0x8000
	s_and_b32 s0, s0, 0x8000
	s_add_i32 s0, s0, 0
	v_add_u32_e32 v80, s0, v210
	s_waitcnt vmcnt(5)
	ds_write_b128 v80, v[132:135]
	v_add_u32_e32 v80, s0, v211
	s_add_i32 s0, s94, 0xffff
	s_mul_i32 s1, s0, 0xab
	s_bfe_u32 s1, s1, 0x70009
	s_mul_i32 s1, s1, 3
	s_sub_i32 s0, s0, s1
	s_and_b32 s0, s0, 0xff
	s_mulk_i32 s0, 0x2400
	s_waitcnt vmcnt(4)
	ds_write_b128 v80, v[128:131]
	v_add_u32_e32 v80, s0, v212
	s_waitcnt vmcnt(3)
	ds_write_b128 v80, v[136:139]
; __device__ __forceinline__ float max3f(float a, float b, float c) { return __builtin_fmaxf(__builtin_fmaxf(a, b), c); }
; __device__ __forceinline__ void rowmax_adjust(f32x16& p0, f32x16& p1, float& m2, f32x16& negm, float& alpha, const bool first) {
;     constexpr float THR2 = THR * 1.4426950408889634f;
;     float pmax = max3f(p0[0], p0[1], p0[2]);
; #pragma unroll
;     for (int r = 3; r < 15; r += 2) pmax = max3f(pmax, p0[r], p0[r + 1]);
;     pmax = max3f(pmax, p0[15], p1[0]);
; #pragma unroll
;     for (int r = 1; r < 15; r += 2) pmax = max3f(pmax, p1[r], p1[r + 1]);
;     pmax = fmaxf(pmax, p1[15]);
;     { auto rr = __builtin_amdgcn_permlane32_swap(__float_as_uint(pmax), __float_as_uint(pmax), false, false);
;       pmax = fmaxf(__uint_as_float(rr[0]), __uint_as_float(rr[1])); }
;     if (!first && __builtin_expect(__all(pmax <= THR2), 1)) { alpha = 1.f; }
.LBB0_1164:
	s_min_u32 s0, s95, 0x7f
	s_lshl_b32 s0, s0, 16
	s_add_i32 s16, s0, 0x40000
	s_add_u32 s0, s58, s16
	s_addc_u32 s1, s59, 0
	global_load_dwordx4 v[132:135], v200, s[0:1]
	global_load_dwordx4 v[128:131], v202, s[0:1]
	v_lshl_add_u64 v[80:81], v[204:205], 0, s[16:17]
	global_load_dwordx4 v[136:139], v[80:81], off
	s_waitcnt lgkmcnt(0)
	s_barrier
	s_or_b32 s0, s95, 1
	s_and_b32 s1, s0, 0xff
	s_mulk_i32 s1, 0xab
	s_bfe_u32 s1, s1, 0x70009
	s_mul_i32 s1, s1, 3
	s_sub_i32 s0, s0, s1
	s_and_b32 s0, s0, 0xff
	s_mulk_i32 s0, 0x2400
	v_add_u32_e32 v84, s0, v218
	s_and_b32 s0, s51, 0x8000
	v_add_u32_e32 v187, s0, v217
	ds_read_b128 v[80:83], v84
	ds_read_b128 v[192:195], v84 offset:4608
	ds_read_b128 v[188:191], v84 offset:32
	ds_read_b128 v[196:199], v84 offset:4640
	ds_read_b128 v[220:223], v84 offset:64
	ds_read_b128 v[228:231], v84 offset:4672
	ds_read_b128 v[224:227], v84 offset:96
	ds_read_b128 v[232:235], v84 offset:4704
	ds_read_b64_tr_b16 v[164:165], v187 offset:0
	ds_read_b64_tr_b16 v[166:167], v187 offset:0x800
	ds_read_b64_tr_b16 v[160:161], v187 offset:0x1000
	ds_read_b64_tr_b16 v[162:163], v187 offset:0x1800
	ds_read_b64_tr_b16 v[156:157], v187 offset:0x2000
	ds_read_b64_tr_b16 v[158:159], v187 offset:0x2800
	ds_read_b64_tr_b16 v[152:153], v187 offset:0x3000
	ds_read_b64_tr_b16 v[154:155], v187 offset:0x3800
	s_waitcnt lgkmcnt(15)
	v_mfma_f32_32x32x16_bf16 v[96:111], v[80:83], v[112:115], v[64:79]
	s_waitcnt lgkmcnt(14)
	v_mfma_f32_32x32x16_bf16 v[80:95], v[192:195], v[112:115], v[64:79]
	s_waitcnt lgkmcnt(13)
	v_mfma_f32_32x32x16_bf16 v[96:111], v[188:191], v[116:119], v[96:111]
	s_waitcnt lgkmcnt(12)
	v_mfma_f32_32x32x16_bf16 v[80:95], v[196:199], v[116:119], v[80:95]
	s_waitcnt lgkmcnt(8)
	ds_read_b64_tr_b16 v[188:189], v187 offset:0x200
	ds_read_b64_tr_b16 v[190:191], v187 offset:0xa00
	ds_read_b64_tr_b16 v[192:193], v187 offset:0x1200
	ds_read_b64_tr_b16 v[194:195], v187 offset:0x1a00
	ds_read_b64_tr_b16 v[196:197], v187 offset:0x2200
	ds_read_b64_tr_b16 v[198:199], v187 offset:0x2a00
	ds_read_b64_tr_b16 v[236:237], v187 offset:0x3200
	ds_read_b64_tr_b16 v[238:239], v187 offset:0x3a00
	v_mfma_f32_32x32x16_bf16 v[96:111], v[220:223], v[120:123], v[96:111]
	v_mfma_f32_32x32x16_bf16 v[80:95], v[228:231], v[120:123], v[80:95]
	v_mfma_f32_32x32x16_bf16 v[96:111], v[224:227], v[124:127], v[96:111]
	v_mfma_f32_32x32x16_bf16 v[80:95], v[232:235], v[124:127], v[80:95]
	ds_read_b64_tr_b16 v[220:221], v187 offset:0x600
	ds_read_b64_tr_b16 v[222:223], v187 offset:0xe00
	ds_read_b64_tr_b16 v[224:225], v187 offset:0x1600
	ds_read_b64_tr_b16 v[226:227], v187 offset:0x1e00
	ds_read_b64_tr_b16 v[228:229], v187 offset:0x2600
	ds_read_b64_tr_b16 v[230:231], v187 offset:0x2e00
	ds_read_b64_tr_b16 v[232:233], v187 offset:0x3600
	ds_read_b64_tr_b16 v[234:235], v187 offset:0x3e00
	s_waitcnt lgkmcnt(15)
	v_mfma_f32_32x32x16_bf16 v[48:63], v[180:183], v[164:167], v[48:63]
	v_mfma_f32_32x32x16_bf16 v[48:63], v[176:179], v[160:163], v[48:63]
	v_mfma_f32_32x32x16_bf16 v[48:63], v[172:175], v[156:159], v[48:63]
	v_mfma_f32_32x32x16_bf16 v[48:63], v[168:171], v[152:155], v[48:63]
	ds_read_b64_tr_b16 v[164:165], v187 offset:0x400
	ds_read_b64_tr_b16 v[166:167], v187 offset:0xc00
	ds_read_b64_tr_b16 v[160:161], v187 offset:0x1400
	ds_read_b64_tr_b16 v[162:163], v187 offset:0x1c00
	ds_read_b64_tr_b16 v[156:157], v187 offset:0x2400
	ds_read_b64_tr_b16 v[158:159], v187 offset:0x2c00
	ds_read_b64_tr_b16 v[152:153], v187 offset:0x3400
	ds_read_b64_tr_b16 v[154:155], v187 offset:0x3c00
	s_waitcnt lgkmcnt(15)
	v_mfma_f32_32x32x16_bf16 v[32:47], v[180:183], v[188:191], v[32:47]
	v_mfma_f32_32x32x16_bf16 v[32:47], v[176:179], v[192:195], v[32:47]
	v_mfma_f32_32x32x16_bf16 v[32:47], v[172:175], v[196:199], v[32:47]
	v_mfma_f32_32x32x16_bf16 v[32:47], v[168:171], v[236:239], v[32:47]
	s_waitcnt lgkmcnt(8)
	v_mfma_f32_32x32x16_bf16 v[0:15], v[180:183], v[220:223], v[0:15]
	v_mfma_f32_32x32x16_bf16 v[0:15], v[176:179], v[224:227], v[0:15]
	v_mfma_f32_32x32x16_bf16 v[0:15], v[172:175], v[228:231], v[0:15]
	v_mfma_f32_32x32x16_bf16 v[0:15], v[168:171], v[232:235], v[0:15]
	s_waitcnt lgkmcnt(0)
	v_mfma_f32_32x32x16_bf16 v[16:31], v[180:183], v[164:167], v[16:31]
	v_mfma_f32_32x32x16_bf16 v[16:31], v[176:179], v[160:163], v[16:31]
	v_mfma_f32_32x32x16_bf16 v[16:31], v[172:175], v[156:159], v[16:31]
	v_mfma_f32_32x32x16_bf16 v[16:31], v[168:171], v[152:155], v[16:31]
	s_barrier
	v_max3_f32 v168, v96, v97, v98
	v_exp_f32_e32 v240, v96
	v_max3_f32 v169, v81, v82, v83
	v_exp_f32_e32 v241, v97
	v_max3_f32 v168, v168, v99, v100
	v_exp_f32_e32 v242, v98
	v_max3_f32 v169, v169, v84, v85
	v_exp_f32_e32 v243, v99
	v_max3_f32 v168, v168, v101, v102
	v_exp_f32_e32 v244, v100
	v_max3_f32 v169, v169, v86, v87
	v_exp_f32_e32 v245, v101
	v_max3_f32 v168, v168, v103, v104
	v_exp_f32_e32 v246, v102
	v_max3_f32 v169, v169, v88, v89
	v_exp_f32_e32 v247, v103
	v_max3_f32 v168, v168, v105, v106
	v_exp_f32_e32 v248, v104
	v_max3_f32 v169, v169, v90, v91
	v_exp_f32_e32 v249, v105
	v_max3_f32 v168, v168, v107, v108
	v_exp_f32_e32 v250, v106
	v_max3_f32 v169, v169, v92, v93
	v_exp_f32_e32 v251, v107
	v_max3_f32 v168, v168, v109, v110
	v_exp_f32_e32 v252, v108
	v_max3_f32 v169, v169, v94, v95
	v_exp_f32_e32 v253, v109
	v_max3_f32 v168, v168, v111, v80
	v_exp_f32_e32 v236, v110
	v_max_f32_e32 v168, v168, v169
	v_exp_f32_e32 v237, v111
	v_mov_b32_e32 v169, v168
	s_nop 1
	v_permlane32_swap_b32_e32 v168, v169
	v_max_f32_e32 v168, v168, v169
	v_cmp_ge_f32_e32 vcc, s83, v168
	v_mov_b32_e32 v187, 1.0
	s_cmp_eq_u64 vcc, exec
	s_cbranch_scc1 .Lsp_do0
	s_branch .LBB0_1171

; #define SBAR() __builtin_amdgcn_sched_barrier(0)
; #define PK4(P, BASE, OUT) do { u32x4 w = {cvtpk_a(P[BASE + 0], P[BASE + 1]), cvtpk_a(P[BASE + 2], P[BASE + 3]), cvtpk_a(P[BASE + 4], P[BASE + 5]), cvtpk_a(P[BASE + 6], P[BASE + 7])}; \
;     OUT = *reinterpret_cast<bf16x8*>(&w); } while (0)
; #define SWAIT() asm volatile("s_waitcnt vmcnt(3)" ::: "memory")
; __device__ __forceinline__ float exp_pack(f32x16& p0, f32x16& p1, bf16x8& pa0, bf16x8& pa1, bf16x8& pa2, bf16x8& pa3) {
; #pragma unroll
;     for (int r = 0; r < 16; ++r) p0[r] = __builtin_amdgcn_exp2f(p0[r]);
; #pragma unroll
;     for (int r = 0; r < 16; ++r) p1[r] = __builtin_amdgcn_exp2f(p1[r]);
;     SBAR(); asm volatile("s_nop 1" ::: "memory"); SBAR();
;     ...
;     PK4(p0, 0, pa0); PK4(p0, 8, pa1); PK4(p1, 0, pa2); PK4(p1, 8, pa3);
;     ...
;     float ps0 = p0[0], ps1 = p1[0];
; #pragma unroll
;     for (int r = 1; r < 16; ++r) { ps0 += p0[r]; ps1 += p1[r]; }
;     float ps = ps0 + ps1;
;     { auto rr = __builtin_amdgcn_permlane32_swap(__float_as_uint(ps), __float_as_uint(ps), false, false);
;       ps = __uint_as_float(rr[0]) + __uint_as_float(rr[1]); }
;     return ps;
; template <bool MLA>
; __device__ __forceinline__ void attn_core(const bf16_t* __restrict__ Qb, const bf16_t* __restrict__ Kh, const bf16_t* __restrict__ Vh, int seq, char* lds,
;                                           f32x16 (&o)[Cfg<MLA>::NCB], const int wid  , const int g  ) {
;     ...
;         SWAIT(); if (j + 3 < NT) SWRITE(((j + 3) % 3) * SHM_K, ((j + 3) & 3) * SHM_V, SO);
.Lsp_do0:
	v_exp_f32_e32 v80, v80
	v_cvt_pk_bf16_f32 v180, v240, v241
	v_cvt_pk_bf16_f32 v176, v248, v249
	v_exp_f32_e32 v81, v81
	v_add_f32_e32 v240, v240, v241
	v_exp_f32_e32 v82, v82
	v_add_f32_e32 v248, v248, v249
	v_add_f32_e32 v240, v242, v240
	v_exp_f32_e32 v83, v83
	v_add_f32_e32 v248, v250, v248
	v_exp_f32_e32 v84, v84
	v_cvt_pk_bf16_f32 v181, v242, v243
	v_add_f32_e32 v240, v243, v240
	v_exp_f32_e32 v85, v85
	v_add_f32_e32 v248, v251, v248
	v_exp_f32_e32 v86, v86
	v_cvt_pk_bf16_f32 v177, v250, v251
	v_add_f32_e32 v240, v244, v240
	v_exp_f32_e32 v87, v87
	v_add_f32_e32 v248, v252, v248
	v_exp_f32_e32 v88, v88
	v_cvt_pk_bf16_f32 v182, v244, v245
	v_add_f32_e32 v240, v245, v240
	v_exp_f32_e32 v89, v89
	v_add_f32_e32 v248, v253, v248
	v_exp_f32_e32 v90, v90
	v_cvt_pk_bf16_f32 v178, v252, v253
	v_add_f32_e32 v240, v246, v240
	v_exp_f32_e32 v91, v91
	v_add_f32_e32 v248, v236, v248
	v_exp_f32_e32 v92, v92
	v_cvt_pk_bf16_f32 v183, v246, v247
	v_add_f32_e32 v240, v247, v240
	v_exp_f32_e32 v93, v93
	v_add_f32_e32 v248, v237, v248
	v_exp_f32_e32 v94, v94
	v_cvt_pk_bf16_f32 v179, v236, v237
	v_add_f32_e32 v240, v240, v248
	v_exp_f32_e32 v95, v95
	v_cvt_pk_bf16_f32 v172, v80, v81
	v_cvt_pk_bf16_f32 v168, v88, v89
	v_add_f32_e32 v80, v80, v81
	v_add_f32_e32 v88, v88, v89
	v_add_f32_e32 v80, v82, v80
	v_add_f32_e32 v88, v90, v88
	v_cvt_pk_bf16_f32 v173, v82, v83
	v_add_f32_e32 v80, v83, v80
	v_add_f32_e32 v88, v91, v88
	v_cvt_pk_bf16_f32 v169, v90, v91
	v_add_f32_e32 v80, v84, v80
	v_add_f32_e32 v88, v92, v88
	v_cvt_pk_bf16_f32 v174, v84, v85
	v_add_f32_e32 v80, v85, v80
	v_add_f32_e32 v88, v93, v88
	v_cvt_pk_bf16_f32 v170, v92, v93
	v_add_f32_e32 v80, v86, v80
	v_add_f32_e32 v88, v94, v88
	v_cvt_pk_bf16_f32 v175, v86, v87
	v_add_f32_e32 v80, v87, v80
	v_add_f32_e32 v88, v95, v88
	v_cvt_pk_bf16_f32 v171, v94, v95
	v_add_f32_e32 v80, v80, v88
	v_add_f32_e32 v80, v80, v240
	s_waitcnt vmcnt(3)
	s_cmpk_gt_u32 s95, 0x80
	s_cbranch_scc1 .LBB0_1149
	s_add_i32 s0, s96, 0
	v_add_u32_e32 v82, s0, v210
	s_waitcnt vmcnt(5)
	ds_write_b128 v82, v[140:143]
	v_add_u32_e32 v82, s0, v211
	s_mul_i32 s0, s94, 0xab
	s_bfe_u32 s0, s0, 0x70009
	s_mul_i32 s0, s0, 3
	s_sub_i32 s0, s94, s0
	s_and_b32 s0, s0, 0xff
	s_mulk_i32 s0, 0x2400
	s_waitcnt vmcnt(4)
	ds_write_b128 v82, v[144:147]
	v_add_u32_e32 v82, s0, v212
	s_waitcnt vmcnt(3)
	ds_write_b128 v82, v[148:151]
	s_branch .LBB0_1149

; __device__ __forceinline__ float max3f(float a, float b, float c) { return __builtin_fmaxf(__builtin_fmaxf(a, b), c); }
; __device__ __forceinline__ void rowmax_adjust(f32x16& p0, f32x16& p1, float& m2, f32x16& negm, float& alpha, const bool first) {
;     ...
;     float pmax = max3f(p0[0], p0[1], p0[2]);
; #pragma unroll
;     for (int r = 3; r < 15; r += 2) pmax = max3f(pmax, p0[r], p0[r + 1]);
;     pmax = max3f(pmax, p0[15], p1[0]);
; #pragma unroll
;     for (int r = 1; r < 15; r += 2) pmax = max3f(pmax, p1[r], p1[r + 1]);
;     pmax = fmaxf(pmax, p1[15]);
;     { auto rr = __builtin_amdgcn_permlane32_swap(__float_as_uint(pmax), __float_as_uint(pmax), false, false);
;       pmax = fmaxf(__uint_as_float(rr[0]), __uint_as_float(rr[1])); }
;     if (!first && __builtin_expect(__all(pmax <= THR2), 1)) { alpha = 1.f; }
; template <bool MLA>
; __device__ __forceinline__ void attn_core(const bf16_t* __restrict__ Qb, const bf16_t* __restrict__ Kh, const bf16_t* __restrict__ Vh, int seq, char* lds,
;                                           f32x16 (&o)[Cfg<MLA>::NCB], const int wid  , const int g  ) {
;     ...
;         __syncthreads();
.Ld1_b_nopv:
	s_waitcnt lgkmcnt(0)
	s_mov_b64 s[0:1], s[60:61]
	s_barrier
	v_max3_f32 v168, v96, v97, v98
	v_exp_f32_e32 v240, v96
	v_max3_f32 v169, v81, v82, v83
	v_exp_f32_e32 v241, v97
	v_max3_f32 v168, v168, v99, v100
	v_exp_f32_e32 v242, v98
	v_max3_f32 v169, v169, v84, v85
	v_exp_f32_e32 v243, v99
	v_max3_f32 v168, v168, v101, v102
	v_exp_f32_e32 v244, v100
	v_max3_f32 v169, v169, v86, v87
	v_exp_f32_e32 v245, v101
	v_max3_f32 v168, v168, v103, v104
	v_exp_f32_e32 v246, v102
	v_max3_f32 v169, v169, v88, v89
	v_exp_f32_e32 v247, v103
	v_max3_f32 v168, v168, v105, v106
	v_exp_f32_e32 v248, v104
	v_max3_f32 v169, v169, v90, v91
	v_exp_f32_e32 v249, v105
	v_max3_f32 v168, v168, v107, v108
	v_exp_f32_e32 v250, v106
	v_max3_f32 v169, v169, v92, v93
	v_exp_f32_e32 v251, v107
	v_max3_f32 v168, v168, v109, v110
	v_exp_f32_e32 v252, v108
	v_max3_f32 v169, v169, v94, v95
	v_exp_f32_e32 v253, v109
	v_max3_f32 v168, v168, v111, v80
	v_exp_f32_e32 v236, v110
	v_max_f32_e32 v168, v168, v169
	v_exp_f32_e32 v237, v111
	v_mov_b32_e32 v169, v168
	s_nop 1
	v_permlane32_swap_b32_e32 v168, v169
	v_max_f32_e32 v168, v168, v169
	v_cmp_ge_f32_e32 vcc, s83, v168
	v_mov_b32_e32 v184, 1.0
	s_cmp_lg_u64 s[0:1], 0
	s_cbranch_scc1 .Lvt31_first
	s_cmp_lg_u64 vcc, exec
	s_cbranch_scc1 .Lvt31_rare
	s_branch .Lsp_de31

; #define SBAR() __builtin_amdgcn_sched_barrier(0)
; #define PK4(P, BASE, OUT) do { u32x4 w = {cvtpk_a(P[BASE + 0], P[BASE + 1]), cvtpk_a(P[BASE + 2], P[BASE + 3]), cvtpk_a(P[BASE + 4], P[BASE + 5]), cvtpk_a(P[BASE + 6], P[BASE + 7])}; \
;     OUT = *reinterpret_cast<bf16x8*>(&w); } while (0)
; #define SWAIT() asm volatile("s_waitcnt vmcnt(3)" ::: "memory")
; __device__ __forceinline__ float exp_pack(f32x16& p0, f32x16& p1, bf16x8& pa0, bf16x8& pa1, bf16x8& pa2, bf16x8& pa3) {
; #pragma unroll
;     for (int r = 0; r < 16; ++r) p0[r] = __builtin_amdgcn_exp2f(p0[r]);
; #pragma unroll
;     for (int r = 0; r < 16; ++r) p1[r] = __builtin_amdgcn_exp2f(p1[r]);
;     SBAR(); asm volatile("s_nop 1" ::: "memory"); SBAR();
;     ...
;     PK4(p0, 0, pa0); PK4(p0, 8, pa1); PK4(p1, 0, pa2); PK4(p1, 8, pa3);
;     ...
;     float ps0 = p0[0], ps1 = p1[0];
; #pragma unroll
;     for (int r = 1; r < 16; ++r) { ps0 += p0[r]; ps1 += p1[r]; }
;     float ps = ps0 + ps1;
;     { auto rr = __builtin_amdgcn_permlane32_swap(__float_as_uint(ps), __float_as_uint(ps), false, false);
;       ps = __uint_as_float(rr[0]) + __uint_as_float(rr[1]); }
;     return ps;
; template <bool MLA>
; __device__ __forceinline__ void attn_core(const bf16_t* __restrict__ Qb, const bf16_t* __restrict__ Kh, const bf16_t* __restrict__ Vh, int seq, char* lds,
;                                           f32x16 (&o)[Cfg<MLA>::NCB], const int wid  , const int g  ) {
;     ...
;         SWAIT(); if (j + 2 < NT) SWRITE(((j + 2) % 3) * SHM_K, ((j + 2) & 3) * SHM_V, SE);
.Lsp_de31:
	v_exp_f32_e32 v80, v80
	v_cvt_pk_bf16_f32 v180, v240, v241
	v_cvt_pk_bf16_f32 v176, v248, v249
	v_exp_f32_e32 v81, v81
	v_add_f32_e32 v240, v240, v241
	v_exp_f32_e32 v82, v82
	v_add_f32_e32 v248, v248, v249
	v_add_f32_e32 v240, v242, v240
	v_exp_f32_e32 v83, v83
	v_add_f32_e32 v248, v250, v248
	v_exp_f32_e32 v84, v84
	v_cvt_pk_bf16_f32 v181, v242, v243
	v_add_f32_e32 v240, v243, v240
	v_exp_f32_e32 v85, v85
	v_add_f32_e32 v248, v251, v248
	v_exp_f32_e32 v86, v86
	v_cvt_pk_bf16_f32 v177, v250, v251
	v_add_f32_e32 v240, v244, v240
	v_exp_f32_e32 v87, v87
	v_add_f32_e32 v248, v252, v248
	v_exp_f32_e32 v88, v88
	v_cvt_pk_bf16_f32 v182, v244, v245
	v_add_f32_e32 v240, v245, v240
	v_exp_f32_e32 v89, v89
	v_add_f32_e32 v248, v253, v248
	v_exp_f32_e32 v90, v90
	v_cvt_pk_bf16_f32 v178, v252, v253
	v_add_f32_e32 v240, v246, v240
	v_exp_f32_e32 v91, v91
	v_add_f32_e32 v248, v236, v248
	v_exp_f32_e32 v92, v92
	v_cvt_pk_bf16_f32 v183, v246, v247
	v_add_f32_e32 v240, v247, v240
	v_exp_f32_e32 v93, v93
	v_add_f32_e32 v248, v237, v248
	v_exp_f32_e32 v94, v94
	v_cvt_pk_bf16_f32 v179, v236, v237
	v_add_f32_e32 v240, v240, v248
	v_exp_f32_e32 v95, v95
	v_cvt_pk_bf16_f32 v172, v80, v81
	v_cvt_pk_bf16_f32 v168, v88, v89
	v_add_f32_e32 v80, v80, v81
	v_add_f32_e32 v88, v88, v89
	v_add_f32_e32 v80, v82, v80
	v_add_f32_e32 v88, v90, v88
	v_cvt_pk_bf16_f32 v173, v82, v83
	v_add_f32_e32 v80, v83, v80
	v_add_f32_e32 v88, v91, v88
	v_cvt_pk_bf16_f32 v169, v90, v91
	v_add_f32_e32 v80, v84, v80
	v_add_f32_e32 v88, v92, v88
	v_cvt_pk_bf16_f32 v174, v84, v85
	v_add_f32_e32 v80, v85, v80
	v_add_f32_e32 v88, v93, v88
	v_cvt_pk_bf16_f32 v170, v92, v93
	v_add_f32_e32 v80, v86, v80
	v_add_f32_e32 v88, v94, v88
	v_cvt_pk_bf16_f32 v175, v86, v87
	v_add_f32_e32 v80, v87, v80
	v_add_f32_e32 v88, v95, v88
	v_cvt_pk_bf16_f32 v171, v94, v95
	v_add_f32_e32 v80, v80, v88
	v_add_f32_e32 v185, v80, v240
	s_waitcnt vmcnt(3)
	s_cmpk_gt_u32 s64, 0x81
	s_cbranch_scc1 .LBB0_1195
	s_add_i32 s0, s51, 0x8000
	s_and_b32 s0, s0, 0x8000
	s_add_i32 s0, s0, 0
	v_add_u32_e32 v80, s0, v210
	s_waitcnt vmcnt(5)
	ds_write_b128 v80, v[132:135]
	v_add_u32_e32 v80, s0, v211
	s_add_i32 s0, s7, 0xffff
	s_mul_i32 s1, s0, 0xab
	s_bfe_u32 s1, s1, 0x70009
	s_mul_i32 s1, s1, 3
	s_sub_i32 s0, s0, s1
	s_and_b32 s0, s0, 0xff
	s_mulk_i32 s0, 0x2400
	s_waitcnt vmcnt(4)
	ds_write_b128 v80, v[128:131]
	v_add_u32_e32 v80, s0, v212
	s_waitcnt vmcnt(3)
	ds_write_b128 v80, v[136:139]
; __device__ __forceinline__ float max3f(float a, float b, float c) { return __builtin_fmaxf(__builtin_fmaxf(a, b), c); }
; __device__ __forceinline__ void rowmax_adjust(f32x16& p0, f32x16& p1, float& m2, f32x16& negm, float& alpha, const bool first) {
;     constexpr float THR2 = THR * 1.4426950408889634f;
;     float pmax = max3f(p0[0], p0[1], p0[2]);
; #pragma unroll
;     for (int r = 3; r < 15; r += 2) pmax = max3f(pmax, p0[r], p0[r + 1]);
;     pmax = max3f(pmax, p0[15], p1[0]);
; #pragma unroll
;     for (int r = 1; r < 15; r += 2) pmax = max3f(pmax, p1[r], p1[r + 1]);
;     pmax = fmaxf(pmax, p1[15]);
;     { auto rr = __builtin_amdgcn_permlane32_swap(__float_as_uint(pmax), __float_as_uint(pmax), false, false);
;       pmax = fmaxf(__uint_as_float(rr[0]), __uint_as_float(rr[1])); }
;     if (!first && __builtin_expect(__all(pmax <= THR2), 1)) { alpha = 1.f; }
.LBB0_1195:
	s_min_u32 s0, s64, 0x7f
	s_lshl_b32 s0, s0, 16
	s_add_i32 s16, s0, 0x40000
	s_add_u32 s0, s58, s16
	s_addc_u32 s1, s59, 0
	global_load_dwordx4 v[132:135], v200, s[0:1]
	global_load_dwordx4 v[128:131], v202, s[0:1]
	v_lshl_add_u64 v[80:81], v[204:205], 0, s[16:17]
	global_load_dwordx4 v[136:139], v[80:81], off
	s_waitcnt lgkmcnt(0)
	s_barrier
	s_or_b32 s0, s64, 1
	s_and_b32 s1, s0, 0xff
	s_mulk_i32 s1, 0xab
	s_bfe_u32 s1, s1, 0x70009
	s_mul_i32 s1, s1, 3
	s_sub_i32 s0, s0, s1
	s_and_b32 s0, s0, 0xff
	s_mulk_i32 s0, 0x2400
	v_add_u32_e32 v84, s0, v218
	s_and_b32 s0, s51, 0x8000
	v_add_u32_e32 v187, s0, v217
	ds_read_b128 v[80:83], v84
	ds_read_b128 v[192:195], v84 offset:4608
	ds_read_b128 v[188:191], v84 offset:32
	ds_read_b128 v[196:199], v84 offset:4640
	ds_read_b128 v[220:223], v84 offset:64
	ds_read_b128 v[228:231], v84 offset:4672
	ds_read_b128 v[224:227], v84 offset:96
	ds_read_b128 v[232:235], v84 offset:4704
	ds_read_b64_tr_b16 v[164:165], v187 offset:0
	ds_read_b64_tr_b16 v[166:167], v187 offset:0x800
	ds_read_b64_tr_b16 v[160:161], v187 offset:0x1000
	ds_read_b64_tr_b16 v[162:163], v187 offset:0x1800
	ds_read_b64_tr_b16 v[156:157], v187 offset:0x2000
	ds_read_b64_tr_b16 v[158:159], v187 offset:0x2800
	ds_read_b64_tr_b16 v[152:153], v187 offset:0x3000
	ds_read_b64_tr_b16 v[154:155], v187 offset:0x3800
	s_waitcnt lgkmcnt(15)
	v_mfma_f32_32x32x16_bf16 v[96:111], v[80:83], v[112:115], v[64:79]
	s_waitcnt lgkmcnt(14)
	v_mfma_f32_32x32x16_bf16 v[80:95], v[192:195], v[112:115], v[64:79]
	s_waitcnt lgkmcnt(13)
	v_mfma_f32_32x32x16_bf16 v[96:111], v[188:191], v[116:119], v[96:111]
	s_waitcnt lgkmcnt(12)
	v_mfma_f32_32x32x16_bf16 v[80:95], v[196:199], v[116:119], v[80:95]
	s_waitcnt lgkmcnt(8)
	ds_read_b64_tr_b16 v[188:189], v187 offset:0x200
	ds_read_b64_tr_b16 v[190:191], v187 offset:0xa00
	ds_read_b64_tr_b16 v[192:193], v187 offset:0x1200
	ds_read_b64_tr_b16 v[194:195], v187 offset:0x1a00
	ds_read_b64_tr_b16 v[196:197], v187 offset:0x2200
	ds_read_b64_tr_b16 v[198:199], v187 offset:0x2a00
	ds_read_b64_tr_b16 v[236:237], v187 offset:0x3200
	ds_read_b64_tr_b16 v[238:239], v187 offset:0x3a00
	v_mfma_f32_32x32x16_bf16 v[96:111], v[220:223], v[120:123], v[96:111]
	v_mfma_f32_32x32x16_bf16 v[80:95], v[228:231], v[120:123], v[80:95]
	v_mfma_f32_32x32x16_bf16 v[96:111], v[224:227], v[124:127], v[96:111]
	v_mfma_f32_32x32x16_bf16 v[80:95], v[232:235], v[124:127], v[80:95]
	ds_read_b64_tr_b16 v[220:221], v187 offset:0x600
	ds_read_b64_tr_b16 v[222:223], v187 offset:0xe00
	ds_read_b64_tr_b16 v[224:225], v187 offset:0x1600
	ds_read_b64_tr_b16 v[226:227], v187 offset:0x1e00
	ds_read_b64_tr_b16 v[228:229], v187 offset:0x2600
	ds_read_b64_tr_b16 v[230:231], v187 offset:0x2e00
	ds_read_b64_tr_b16 v[232:233], v187 offset:0x3600
	ds_read_b64_tr_b16 v[234:235], v187 offset:0x3e00
	s_waitcnt lgkmcnt(15)
	v_mfma_f32_32x32x16_bf16 v[48:63], v[180:183], v[164:167], v[48:63]
	v_mfma_f32_32x32x16_bf16 v[48:63], v[176:179], v[160:163], v[48:63]
	v_mfma_f32_32x32x16_bf16 v[48:63], v[172:175], v[156:159], v[48:63]
	v_mfma_f32_32x32x16_bf16 v[48:63], v[168:171], v[152:155], v[48:63]
	ds_read_b64_tr_b16 v[164:165], v187 offset:0x400
	ds_read_b64_tr_b16 v[166:167], v187 offset:0xc00
	ds_read_b64_tr_b16 v[160:161], v187 offset:0x1400
	ds_read_b64_tr_b16 v[162:163], v187 offset:0x1c00
	ds_read_b64_tr_b16 v[156:157], v187 offset:0x2400
	ds_read_b64_tr_b16 v[158:159], v187 offset:0x2c00
	ds_read_b64_tr_b16 v[152:153], v187 offset:0x3400
	ds_read_b64_tr_b16 v[154:155], v187 offset:0x3c00
	s_waitcnt lgkmcnt(15)
	v_mfma_f32_32x32x16_bf16 v[32:47], v[180:183], v[188:191], v[32:47]
	v_mfma_f32_32x32x16_bf16 v[32:47], v[176:179], v[192:195], v[32:47]
	v_mfma_f32_32x32x16_bf16 v[32:47], v[172:175], v[196:199], v[32:47]
	v_mfma_f32_32x32x16_bf16 v[32:47], v[168:171], v[236:239], v[32:47]
	s_waitcnt lgkmcnt(8)
	v_mfma_f32_32x32x16_bf16 v[0:15], v[180:183], v[220:223], v[0:15]
	v_mfma_f32_32x32x16_bf16 v[0:15], v[176:179], v[224:227], v[0:15]
	v_mfma_f32_32x32x16_bf16 v[0:15], v[172:175], v[228:231], v[0:15]
	v_mfma_f32_32x32x16_bf16 v[0:15], v[168:171], v[232:235], v[0:15]
	s_waitcnt lgkmcnt(0)
	v_mfma_f32_32x32x16_bf16 v[16:31], v[180:183], v[164:167], v[16:31]
	v_mfma_f32_32x32x16_bf16 v[16:31], v[176:179], v[160:163], v[16:31]
	v_mfma_f32_32x32x16_bf16 v[16:31], v[172:175], v[156:159], v[16:31]
	v_mfma_f32_32x32x16_bf16 v[16:31], v[168:171], v[152:155], v[16:31]
	s_barrier
	v_max3_f32 v168, v96, v97, v98
	v_exp_f32_e32 v240, v96
	v_max3_f32 v169, v81, v82, v83
	v_exp_f32_e32 v241, v97
	v_max3_f32 v168, v168, v99, v100
	v_exp_f32_e32 v242, v98
	v_max3_f32 v169, v169, v84, v85
	v_exp_f32_e32 v243, v99
	v_max3_f32 v168, v168, v101, v102
	v_exp_f32_e32 v244, v100
	v_max3_f32 v169, v169, v86, v87
	v_exp_f32_e32 v245, v101
	v_max3_f32 v168, v168, v103, v104
	v_exp_f32_e32 v246, v102
	v_max3_f32 v169, v169, v88, v89
	v_exp_f32_e32 v247, v103
	v_max3_f32 v168, v168, v105, v106
	v_exp_f32_e32 v248, v104
	v_max3_f32 v169, v169, v90, v91
	v_exp_f32_e32 v249, v105
	v_max3_f32 v168, v168, v107, v108
	v_exp_f32_e32 v250, v106
	v_max3_f32 v169, v169, v92, v93
	v_exp_f32_e32 v251, v107
	v_max3_f32 v168, v168, v109, v110
	v_exp_f32_e32 v252, v108
	v_max3_f32 v169, v169, v94, v95
	v_exp_f32_e32 v253, v109
	v_max3_f32 v168, v168, v111, v80
	v_exp_f32_e32 v236, v110
	v_max_f32_e32 v168, v168, v169
	v_exp_f32_e32 v237, v111
	v_mov_b32_e32 v169, v168
	s_nop 1
	v_permlane32_swap_b32_e32 v168, v169
	v_max_f32_e32 v168, v168, v169
	v_cmp_ge_f32_e32 vcc, s83, v168
	v_mov_b32_e32 v187, 1.0
	s_cmp_eq_u64 vcc, exec
	s_cbranch_scc1 .Lsp_do31
	s_branch .LBB0_1202

; #define SBAR() __builtin_amdgcn_sched_barrier(0)
; #define PK4(P, BASE, OUT) do { u32x4 w = {cvtpk_a(P[BASE + 0], P[BASE + 1]), cvtpk_a(P[BASE + 2], P[BASE + 3]), cvtpk_a(P[BASE + 4], P[BASE + 5]), cvtpk_a(P[BASE + 6], P[BASE + 7])}; \
;     OUT = *reinterpret_cast<bf16x8*>(&w); } while (0)
; #define SWAIT() asm volatile("s_waitcnt vmcnt(3)" ::: "memory")
; __device__ __forceinline__ float exp_pack(f32x16& p0, f32x16& p1, bf16x8& pa0, bf16x8& pa1, bf16x8& pa2, bf16x8& pa3) {
; #pragma unroll
;     for (int r = 0; r < 16; ++r) p0[r] = __builtin_amdgcn_exp2f(p0[r]);
; #pragma unroll
;     for (int r = 0; r < 16; ++r) p1[r] = __builtin_amdgcn_exp2f(p1[r]);
;     SBAR(); asm volatile("s_nop 1" ::: "memory"); SBAR();
;     ...
;     PK4(p0, 0, pa0); PK4(p0, 8, pa1); PK4(p1, 0, pa2); PK4(p1, 8, pa3);
;     ...
;     float ps0 = p0[0], ps1 = p1[0];
; #pragma unroll
;     for (int r = 1; r < 16; ++r) { ps0 += p0[r]; ps1 += p1[r]; }
;     float ps = ps0 + ps1;
;     { auto rr = __builtin_amdgcn_permlane32_swap(__float_as_uint(ps), __float_as_uint(ps), false, false);
;       ps = __uint_as_float(rr[0]) + __uint_as_float(rr[1]); }
;     return ps;
; template <bool MLA>
; __device__ __forceinline__ void attn_core(const bf16_t* __restrict__ Qb, const bf16_t* __restrict__ Kh, const bf16_t* __restrict__ Vh, int seq, char* lds,
;                                           f32x16 (&o)[Cfg<MLA>::NCB], const int wid  , const int g  ) {
;     ...
;         SWAIT(); if (j + 3 < NT) SWRITE(((j + 3) % 3) * SHM_K, ((j + 3) & 3) * SHM_V, SO);
.Lsp_do31:
	v_exp_f32_e32 v80, v80
	v_cvt_pk_bf16_f32 v180, v240, v241
	v_cvt_pk_bf16_f32 v176, v248, v249
	v_exp_f32_e32 v81, v81
	v_add_f32_e32 v240, v240, v241
	v_exp_f32_e32 v82, v82
	v_add_f32_e32 v248, v248, v249
	v_add_f32_e32 v240, v242, v240
	v_exp_f32_e32 v83, v83
	v_add_f32_e32 v248, v250, v248
	v_exp_f32_e32 v84, v84
	v_cvt_pk_bf16_f32 v181, v242, v243
	v_add_f32_e32 v240, v243, v240
	v_exp_f32_e32 v85, v85
	v_add_f32_e32 v248, v251, v248
	v_exp_f32_e32 v86, v86
	v_cvt_pk_bf16_f32 v177, v250, v251
	v_add_f32_e32 v240, v244, v240
	v_exp_f32_e32 v87, v87
	v_add_f32_e32 v248, v252, v248
	v_exp_f32_e32 v88, v88
	v_cvt_pk_bf16_f32 v182, v244, v245
	v_add_f32_e32 v240, v245, v240
	v_exp_f32_e32 v89, v89
	v_add_f32_e32 v248, v253, v248
	v_exp_f32_e32 v90, v90
	v_cvt_pk_bf16_f32 v178, v252, v253
	v_add_f32_e32 v240, v246, v240
	v_exp_f32_e32 v91, v91
	v_add_f32_e32 v248, v236, v248
	v_exp_f32_e32 v92, v92
	v_cvt_pk_bf16_f32 v183, v246, v247
	v_add_f32_e32 v240, v247, v240
	v_exp_f32_e32 v93, v93
	v_add_f32_e32 v248, v237, v248
	v_exp_f32_e32 v94, v94
	v_cvt_pk_bf16_f32 v179, v236, v237
	v_add_f32_e32 v240, v240, v248
	v_exp_f32_e32 v95, v95
	v_cvt_pk_bf16_f32 v172, v80, v81
	v_cvt_pk_bf16_f32 v168, v88, v89
	v_add_f32_e32 v80, v80, v81
	v_add_f32_e32 v88, v88, v89
	v_add_f32_e32 v80, v82, v80
	v_add_f32_e32 v88, v90, v88
	v_cvt_pk_bf16_f32 v173, v82, v83
	v_add_f32_e32 v80, v83, v80
	v_add_f32_e32 v88, v91, v88
	v_cvt_pk_bf16_f32 v169, v90, v91
	v_add_f32_e32 v80, v84, v80
	v_add_f32_e32 v88, v92, v88
	v_cvt_pk_bf16_f32 v174, v84, v85
	v_add_f32_e32 v80, v85, v80
	v_add_f32_e32 v88, v93, v88
	v_cvt_pk_bf16_f32 v170, v92, v93
	v_add_f32_e32 v80, v86, v80
	v_add_f32_e32 v88, v94, v88
	v_cvt_pk_bf16_f32 v175, v86, v87
	v_add_f32_e32 v80, v87, v80
	v_add_f32_e32 v88, v95, v88
	v_cvt_pk_bf16_f32 v171, v94, v95
	v_add_f32_e32 v80, v80, v88
	v_add_f32_e32 v80, v80, v240
	s_waitcnt vmcnt(3)
	s_cmpk_gt_u32 s64, 0x80
	s_cbranch_scc1 .LBB0_1180
	s_add_i32 s0, s65, 0
	v_add_u32_e32 v82, s0, v210
	s_waitcnt vmcnt(5)
	ds_write_b128 v82, v[140:143]
	v_add_u32_e32 v82, s0, v211
	s_mul_i32 s0, s7, 0xab
	s_bfe_u32 s0, s0, 0x70009
	s_mul_i32 s0, s0, 3
	s_sub_i32 s0, s7, s0
	s_and_b32 s0, s0, 0xff
	s_mulk_i32 s0, 0x2400
	s_waitcnt vmcnt(4)
	ds_write_b128 v82, v[144:147]
	v_add_u32_e32 v82, s0, v212
	s_waitcnt vmcnt(3)
	ds_write_b128 v82, v[148:151]
	s_branch .LBB0_1180

; __device__ __forceinline__ float max3f(float a, float b, float c) { return __builtin_fmaxf(__builtin_fmaxf(a, b), c); }
; __device__ __forceinline__ void rowmax_adjust(f32x16& p0, f32x16& p1, float& m2, f32x16& negm, float& alpha, const bool first) {
;     constexpr float THR2 = THR * 1.4426950408889634f;
;     float pmax = max3f(p0[0], p0[1], p0[2]);
; #pragma unroll
;     for (int r = 3; r < 15; r += 2) pmax = max3f(pmax, p0[r], p0[r + 1]);
;     pmax = max3f(pmax, p0[15], p1[0]);
; #pragma unroll
;     for (int r = 1; r < 15; r += 2) pmax = max3f(pmax, p1[r], p1[r + 1]);
;     pmax = fmaxf(pmax, p1[15]);
;     { auto rr = __builtin_amdgcn_permlane32_swap(__float_as_uint(pmax), __float_as_uint(pmax), false, false);
;       pmax = fmaxf(__uint_as_float(rr[0]), __uint_as_float(rr[1])); }
;     if (!first && __builtin_expect(__all(pmax <= THR2), 1)) { alpha = 1.f; }
.LBB0_1228:
	s_add_i32 s61, s51, -3
	s_mul_i32 s10, s61, 0xab
	s_bfe_u32 s10, s10, 0x70009
	s_mul_i32 s10, s10, 3
	s_sub_i32 s10, s61, s10
	s_and_b32 s10, s10, 0xff
	s_mulk_i32 s10, 0x4400
	v_add_u32_e32 v52, s10, v152
	ds_read_b128 v[48:51], v52 offset:32768
	ds_read_b128 v[158:161], v52 offset:32800
	ds_read_b128 v[162:165], v52 offset:41472
	ds_read_b128 v[166:169], v52 offset:41504
	ds_read_b128 v[170:173], v52 offset:32832
	ds_read_b128 v[174:177], v52 offset:32864
	ds_read_b128 v[178:181], v52 offset:41536
	ds_read_b128 v[182:185], v52 offset:41568
	ds_read_b128 v[186:189], v52 offset:32896
	ds_read_b128 v[190:193], v52 offset:32928
	ds_read_b128 v[194:197], v52 offset:41600
	ds_read_b128 v[202:205], v52 offset:41632
	s_waitcnt lgkmcnt(11)
	v_mfma_f32_32x32x16_bf16 v[64:79], v[48:51], v[80:83], v[32:47]
	s_waitcnt lgkmcnt(9)
	v_mfma_f32_32x32x16_bf16 v[48:63], v[162:165], v[80:83], v[32:47]
	v_mfma_f32_32x32x16_bf16 v[64:79], v[158:161], v[84:87], v[64:79]
	s_waitcnt lgkmcnt(8)
	v_mfma_f32_32x32x16_bf16 v[48:63], v[166:169], v[84:87], v[48:63]
	s_waitcnt lgkmcnt(7)
	v_mfma_f32_32x32x16_bf16 v[64:79], v[170:173], v[88:91], v[64:79]
	s_waitcnt lgkmcnt(5)
	v_mfma_f32_32x32x16_bf16 v[48:63], v[178:181], v[88:91], v[48:63]
	s_waitcnt lgkmcnt(4)
	s_waitcnt lgkmcnt(3)
	s_waitcnt lgkmcnt(1)
	s_waitcnt lgkmcnt(0)
	s_and_b32 s62, s60, 0x6000
	v_add_u32_e32 v198, s62, v155
	ds_read_b64_tr_b16 v[158:159], v198 offset:0
	ds_read_b64_tr_b16 v[160:161], v198 offset:0x400
	ds_read_b64_tr_b16 v[162:163], v198 offset:0x800
	ds_read_b64_tr_b16 v[164:165], v198 offset:0xc00
	ds_read_b64_tr_b16 v[166:167], v198 offset:0x1000
	ds_read_b64_tr_b16 v[168:169], v198 offset:0x1400
	ds_read_b64_tr_b16 v[170:171], v198 offset:0x1800
	ds_read_b64_tr_b16 v[172:173], v198 offset:0x1c00
	ds_read_b64_tr_b16 v[178:179], v198 offset:0x200
	ds_read_b64_tr_b16 v[180:181], v198 offset:0x600
	ds_read_b64_tr_b16 v[210:211], v198 offset:0xa00
	ds_read_b64_tr_b16 v[212:213], v198 offset:0xe00
	ds_read_b64_tr_b16 v[214:215], v198 offset:0x1200
	ds_read_b64_tr_b16 v[216:217], v198 offset:0x1600
	ds_read_b64_tr_b16 v[218:219], v198 offset:0x1a00
	ds_read_b64_tr_b16 v[220:221], v198 offset:0x1e00
	s_nop 0
	v_mfma_f32_32x32x16_bf16 v[64:79], v[174:177], v[92:95], v[64:79]
	v_mfma_f32_32x32x16_bf16 v[48:63], v[182:185], v[92:95], v[48:63]
	v_mfma_f32_32x32x16_bf16 v[64:79], v[186:189], v[96:99], v[64:79]
	v_mfma_f32_32x32x16_bf16 v[48:63], v[194:197], v[96:99], v[48:63]
	v_mfma_f32_32x32x16_bf16 v[64:79], v[190:193], v[100:103], v[64:79]
	v_mfma_f32_32x32x16_bf16 v[48:63], v[202:205], v[100:103], v[48:63]
	s_waitcnt lgkmcnt(0)
	v_mfma_f32_32x32x16_bf16 v[0:15], v[140:143], v[158:161], v[0:15]
	v_mfma_f32_32x32x16_bf16 v[16:31], v[140:143], v[178:181], v[16:31]
	v_mfma_f32_32x32x16_bf16 v[0:15], v[136:139], v[162:165], v[0:15]
	v_mfma_f32_32x32x16_bf16 v[16:31], v[136:139], v[210:213], v[16:31]
	v_mfma_f32_32x32x16_bf16 v[0:15], v[132:135], v[166:169], v[0:15]
	v_mfma_f32_32x32x16_bf16 v[16:31], v[132:135], v[214:217], v[16:31]
	v_mfma_f32_32x32x16_bf16 v[0:15], v[128:131], v[170:173], v[0:15]
	v_mfma_f32_32x32x16_bf16 v[16:31], v[128:131], v[218:221], v[16:31]
	s_barrier
	s_nop 1
	v_max3_f32 v128, v64, v65, v66
	v_exp_f32_e32 v226, v64
	v_max3_f32 v129, v49, v50, v51
	v_exp_f32_e32 v227, v65
	v_max3_f32 v128, v128, v67, v68
	v_exp_f32_e32 v228, v66
	v_max3_f32 v129, v129, v52, v53
	v_exp_f32_e32 v229, v67
	v_max3_f32 v128, v128, v69, v70
	v_exp_f32_e32 v230, v68
	v_max3_f32 v129, v129, v54, v55
	v_exp_f32_e32 v231, v69
	v_max3_f32 v128, v128, v71, v72
	v_exp_f32_e32 v232, v70
	v_max3_f32 v129, v129, v56, v57
	v_exp_f32_e32 v233, v71
	v_max3_f32 v128, v128, v73, v74
	v_exp_f32_e32 v234, v72
	v_max3_f32 v129, v129, v58, v59
	v_exp_f32_e32 v235, v73
	v_max3_f32 v128, v128, v75, v76
	v_exp_f32_e32 v236, v74
	v_max3_f32 v129, v129, v60, v61
	v_exp_f32_e32 v237, v75
	v_max3_f32 v128, v128, v77, v78
	v_exp_f32_e32 v238, v76
	v_max3_f32 v129, v129, v62, v63
	v_exp_f32_e32 v239, v77
	v_max3_f32 v128, v128, v79, v48
	v_exp_f32_e32 v240, v78
	v_max_f32_e32 v128, v128, v129
	v_exp_f32_e32 v241, v79
	v_mov_b32_e32 v129, v128
	s_nop 1
	v_permlane32_swap_b32_e32 v128, v129
	v_max_f32_e32 v128, v128, v129
	v_cmp_ge_f32_e32 vcc, s83, v128
	v_mov_b32_e32 v158, 1.0
	s_cmp_eq_u64 vcc, exec
	s_cbranch_scc1 .Lsp_me
	s_branch .LBB0_1244

; #define SBAR() __builtin_amdgcn_sched_barrier(0)
; #define PK4(P, BASE, OUT) do { u32x4 w = {cvtpk_a(P[BASE + 0], P[BASE + 1]), cvtpk_a(P[BASE + 2], P[BASE + 3]), cvtpk_a(P[BASE + 4], P[BASE + 5]), cvtpk_a(P[BASE + 6], P[BASE + 7])}; \
;     OUT = *reinterpret_cast<bf16x8*>(&w); } while (0)
; #define SWAIT() asm volatile("s_waitcnt vmcnt(3)" ::: "memory")
; __device__ __forceinline__ float exp_pack(f32x16& p0, f32x16& p1, bf16x8& pa0, bf16x8& pa1, bf16x8& pa2, bf16x8& pa3) {
; #pragma unroll
;     for (int r = 0; r < 16; ++r) p0[r] = __builtin_amdgcn_exp2f(p0[r]);
; #pragma unroll
;     for (int r = 0; r < 16; ++r) p1[r] = __builtin_amdgcn_exp2f(p1[r]);
;     SBAR(); asm volatile("s_nop 1" ::: "memory"); SBAR();
;     ...
;     PK4(p0, 0, pa0); PK4(p0, 8, pa1); PK4(p1, 0, pa2); PK4(p1, 8, pa3);
;     ...
;     float ps0 = p0[0], ps1 = p1[0];
; #pragma unroll
;     for (int r = 1; r < 16; ++r) { ps0 += p0[r]; ps1 += p1[r]; }
;     float ps = ps0 + ps1;
;     { auto rr = __builtin_amdgcn_permlane32_swap(__float_as_uint(ps), __float_as_uint(ps), false, false);
;       ps = __uint_as_float(rr[0]) + __uint_as_float(rr[1]); }
;     return ps;
; template <bool MLA>
; __device__ __forceinline__ void attn_core(const bf16_t* __restrict__ Qb, const bf16_t* __restrict__ Kh, const bf16_t* __restrict__ Vh, int seq, char* lds,
;                                           f32x16 (&o)[Cfg<MLA>::NCB], const int wid  , const int g  ) {
;     ...
;         SWAIT(); if (j + 2 < NT) SWRITE(((j + 2) % 3) * SHM_K, ((j + 2) & 3) * SHM_V, SE);
.LBB0_1233:
	v_exp_f32_e32 v226, v64
	v_exp_f32_e32 v227, v65
	v_exp_f32_e32 v228, v66
	v_exp_f32_e32 v229, v67
	v_exp_f32_e32 v230, v68
	v_exp_f32_e32 v231, v69
	v_exp_f32_e32 v232, v70
	v_exp_f32_e32 v233, v71
	v_exp_f32_e32 v234, v72
	v_exp_f32_e32 v235, v73
	v_exp_f32_e32 v236, v74
	v_exp_f32_e32 v237, v75
	v_exp_f32_e32 v238, v76
	v_exp_f32_e32 v239, v77
	v_exp_f32_e32 v240, v78
	v_exp_f32_e32 v241, v79
.Lsp_me:
	v_exp_f32_e32 v48, v48
	v_cvt_pk_bf16_f32 v140, v226, v227
	v_cvt_pk_bf16_f32 v136, v234, v235
	v_exp_f32_e32 v49, v49
	v_add_f32_e32 v226, v226, v227
	v_exp_f32_e32 v50, v50
	v_add_f32_e32 v234, v234, v235
	v_add_f32_e32 v226, v228, v226
	v_exp_f32_e32 v51, v51
	v_add_f32_e32 v234, v236, v234
	v_exp_f32_e32 v52, v52
	v_cvt_pk_bf16_f32 v141, v228, v229
	v_add_f32_e32 v226, v229, v226
	v_exp_f32_e32 v53, v53
	v_add_f32_e32 v234, v237, v234
	v_exp_f32_e32 v54, v54
	v_cvt_pk_bf16_f32 v137, v236, v237
	v_add_f32_e32 v226, v230, v226
	v_exp_f32_e32 v55, v55
	v_add_f32_e32 v234, v238, v234
	v_exp_f32_e32 v56, v56
	v_cvt_pk_bf16_f32 v142, v230, v231
	v_add_f32_e32 v226, v231, v226
	v_exp_f32_e32 v57, v57
	v_add_f32_e32 v234, v239, v234
	v_exp_f32_e32 v58, v58
	v_cvt_pk_bf16_f32 v138, v238, v239
	v_add_f32_e32 v226, v232, v226
	v_exp_f32_e32 v59, v59
	v_add_f32_e32 v234, v240, v234
	v_exp_f32_e32 v60, v60
	v_cvt_pk_bf16_f32 v143, v232, v233
	v_add_f32_e32 v226, v233, v226
	v_exp_f32_e32 v61, v61
	v_add_f32_e32 v234, v241, v234
	v_exp_f32_e32 v62, v62
	v_cvt_pk_bf16_f32 v139, v240, v241
	v_add_f32_e32 v226, v226, v234
	v_exp_f32_e32 v63, v63
	v_cvt_pk_bf16_f32 v132, v48, v49
	v_cvt_pk_bf16_f32 v128, v56, v57
	v_add_f32_e32 v48, v48, v49
	v_add_f32_e32 v56, v56, v57
	v_add_f32_e32 v48, v50, v48
	v_add_f32_e32 v56, v58, v56
	v_cvt_pk_bf16_f32 v133, v50, v51
	v_add_f32_e32 v48, v51, v48
	v_add_f32_e32 v56, v59, v56
	v_cvt_pk_bf16_f32 v129, v58, v59
	v_add_f32_e32 v48, v52, v48
	v_add_f32_e32 v56, v60, v56
	v_cvt_pk_bf16_f32 v134, v52, v53
	v_add_f32_e32 v48, v53, v48
	v_add_f32_e32 v56, v61, v56
	v_cvt_pk_bf16_f32 v130, v60, v61
	v_add_f32_e32 v48, v54, v48
	v_add_f32_e32 v56, v62, v56
	v_cvt_pk_bf16_f32 v135, v54, v55
	v_add_f32_e32 v48, v55, v48
	v_add_f32_e32 v56, v63, v56
	v_cvt_pk_bf16_f32 v131, v62, v63
	v_add_f32_e32 v48, v48, v56
	v_add_f32_e32 v159, v48, v226
	s_waitcnt vmcnt(3)
	s_cmpk_gt_u32 s61, 0x81
	s_cbranch_scc1 .LBB0_1236
	s_add_i32 s10, s60, 0xffffe000
	s_and_b32 s10, s10, 0x4000
	v_add_u32_e32 v48, s10, v145
	s_add_i32 s10, s51, 0xffff
	s_mul_i32 s11, s10, 0xab
	s_bfe_u32 s11, s11, 0x70009
	s_mul_i32 s11, s11, 3
	s_sub_i32 s10, s10, s11
	s_and_b32 s10, s10, 0xff
	s_mulk_i32 s10, 0x4400
	s_add_i32 s16, s10, 0
	s_waitcnt vmcnt(5)
	ds_write_b128 v48, v[112:115]
	v_add_u32_e32 v48, s16, v144
	s_and_b64 vcc, exec, s[4:5]
	s_waitcnt vmcnt(4)
	ds_write_b128 v48, v[108:111] offset:32768
	s_cbranch_vccnz .LBB0_1236
	v_add_u32_e32 v48, s16, v150
	s_waitcnt vmcnt(3)
	ds_write_b128 v48, v[104:107] offset:32768
; __device__ __forceinline__ float max3f(float a, float b, float c) { return __builtin_fmaxf(__builtin_fmaxf(a, b), c); }
; __device__ __forceinline__ void rowmax_adjust(f32x16& p0, f32x16& p1, float& m2, f32x16& negm, float& alpha, const bool first) {
;     constexpr float THR2 = THR * 1.4426950408889634f;
;     float pmax = max3f(p0[0], p0[1], p0[2]);
; #pragma unroll
;     for (int r = 3; r < 15; r += 2) pmax = max3f(pmax, p0[r], p0[r + 1]);
;     pmax = max3f(pmax, p0[15], p1[0]);
; #pragma unroll
;     for (int r = 1; r < 15; r += 2) pmax = max3f(pmax, p1[r], p1[r + 1]);
;     pmax = fmaxf(pmax, p1[15]);
;     { auto rr = __builtin_amdgcn_permlane32_swap(__float_as_uint(pmax), __float_as_uint(pmax), false, false);
;       pmax = fmaxf(__uint_as_float(rr[0]), __uint_as_float(rr[1])); }
;     if (!first && __builtin_expect(__all(pmax <= THR2), 1)) { alpha = 1.f; }
.LBB0_1236:
	s_min_u32 s10, s61, 0x7f
	s_lshl_b32 s10, s10, 6
	s_add_i32 s16, s10, 0x100
	s_add_i32 s38, s60, 0xffffa000
	s_mul_i32 s10, s16, 0x600
	s_add_u32 s10, s58, s10
	s_addc_u32 s11, s59, 0
	s_lshl_b32 s16, s16, 10
	v_lshl_add_u64 v[48:49], v[148:149], 0, s[16:17]
	global_load_dwordx4 v[112:115], v[48:49], off
	global_load_dwordx4 v[108:111], v146, s[10:11]
	global_load_dwordx4 v[104:107], v200, s[10:11]
	s_waitcnt lgkmcnt(0)
	s_barrier
	s_or_b32 s10, s61, 1
	s_and_b32 s11, s10, 0xff
	s_mulk_i32 s11, 0xab
	s_bfe_u32 s11, s11, 0x70009
	s_mul_i32 s11, s11, 3
	s_sub_i32 s10, s10, s11
	s_and_b32 s10, s10, 0xff
	s_mulk_i32 s10, 0x4400
	v_add_u32_e32 v52, s10, v152
	ds_read_b128 v[48:51], v52 offset:32768
	ds_read_b128 v[162:165], v52 offset:32800
	ds_read_b128 v[166:169], v52 offset:41472
	ds_read_b128 v[170:173], v52 offset:41504
	ds_read_b128 v[174:177], v52 offset:32832
	ds_read_b128 v[178:181], v52 offset:32864
	ds_read_b128 v[182:185], v52 offset:41536
	ds_read_b128 v[186:189], v52 offset:41568
	ds_read_b128 v[190:193], v52 offset:32896
	ds_read_b128 v[194:197], v52 offset:32928
	ds_read_b128 v[202:205], v52 offset:41600
	ds_read_b128 v[210:213], v52 offset:41632
	s_and_b32 s10, s38, 0x4000
	s_waitcnt lgkmcnt(11)
	v_mfma_f32_32x32x16_bf16 v[64:79], v[48:51], v[80:83], v[32:47]
	s_waitcnt lgkmcnt(9)
	v_mfma_f32_32x32x16_bf16 v[48:63], v[166:169], v[80:83], v[32:47]
	v_mfma_f32_32x32x16_bf16 v[64:79], v[162:165], v[84:87], v[64:79]
	s_waitcnt lgkmcnt(8)
	v_mfma_f32_32x32x16_bf16 v[48:63], v[170:173], v[84:87], v[48:63]
	s_waitcnt lgkmcnt(7)
	v_mfma_f32_32x32x16_bf16 v[64:79], v[174:177], v[88:91], v[64:79]
	s_waitcnt lgkmcnt(5)
	v_mfma_f32_32x32x16_bf16 v[48:63], v[182:185], v[88:91], v[48:63]
	v_add_u32_e32 v161, s10, v155
	s_waitcnt lgkmcnt(4)
	s_waitcnt lgkmcnt(3)
	s_waitcnt lgkmcnt(1)
	s_waitcnt lgkmcnt(0)
	ds_read_b64_tr_b16 v[162:163], v161 offset:0
	ds_read_b64_tr_b16 v[164:165], v161 offset:0x400
	ds_read_b64_tr_b16 v[166:167], v161 offset:0x800
	ds_read_b64_tr_b16 v[168:169], v161 offset:0xc00
	ds_read_b64_tr_b16 v[170:171], v161 offset:0x1000
	ds_read_b64_tr_b16 v[172:173], v161 offset:0x1400
	ds_read_b64_tr_b16 v[174:175], v161 offset:0x1800
	ds_read_b64_tr_b16 v[176:177], v161 offset:0x1c00
	ds_read_b64_tr_b16 v[182:183], v161 offset:0x200
	ds_read_b64_tr_b16 v[184:185], v161 offset:0x600
	ds_read_b64_tr_b16 v[214:215], v161 offset:0xa00
	ds_read_b64_tr_b16 v[216:217], v161 offset:0xe00
	ds_read_b64_tr_b16 v[218:219], v161 offset:0x1200
	ds_read_b64_tr_b16 v[220:221], v161 offset:0x1600
	ds_read_b64_tr_b16 v[222:223], v161 offset:0x1a00
	ds_read_b64_tr_b16 v[224:225], v161 offset:0x1e00
	s_nop 0
	v_mfma_f32_32x32x16_bf16 v[64:79], v[178:181], v[92:95], v[64:79]
	v_mfma_f32_32x32x16_bf16 v[48:63], v[186:189], v[92:95], v[48:63]
	v_mfma_f32_32x32x16_bf16 v[64:79], v[190:193], v[96:99], v[64:79]
	v_mfma_f32_32x32x16_bf16 v[48:63], v[202:205], v[96:99], v[48:63]
	v_mfma_f32_32x32x16_bf16 v[64:79], v[194:197], v[100:103], v[64:79]
	v_mfma_f32_32x32x16_bf16 v[48:63], v[210:213], v[100:103], v[48:63]
	s_waitcnt lgkmcnt(0)
	v_mfma_f32_32x32x16_bf16 v[0:15], v[140:143], v[162:165], v[0:15]
	v_mfma_f32_32x32x16_bf16 v[16:31], v[140:143], v[182:185], v[16:31]
	v_mfma_f32_32x32x16_bf16 v[0:15], v[136:139], v[166:169], v[0:15]
	v_mfma_f32_32x32x16_bf16 v[16:31], v[136:139], v[214:217], v[16:31]
	v_mfma_f32_32x32x16_bf16 v[0:15], v[132:135], v[170:173], v[0:15]
	v_mfma_f32_32x32x16_bf16 v[16:31], v[132:135], v[218:221], v[16:31]
	v_mfma_f32_32x32x16_bf16 v[0:15], v[128:131], v[174:177], v[0:15]
	v_mfma_f32_32x32x16_bf16 v[16:31], v[128:131], v[222:225], v[16:31]
	s_barrier
	s_nop 1
	v_max3_f32 v128, v64, v65, v66
	v_exp_f32_e32 v226, v64
	v_max3_f32 v129, v49, v50, v51
	v_exp_f32_e32 v227, v65
	v_max3_f32 v128, v128, v67, v68
	v_exp_f32_e32 v228, v66
	v_max3_f32 v129, v129, v52, v53
	v_exp_f32_e32 v229, v67
	v_max3_f32 v128, v128, v69, v70
	v_exp_f32_e32 v230, v68
	v_max3_f32 v129, v129, v54, v55
	v_exp_f32_e32 v231, v69
	v_max3_f32 v128, v128, v71, v72
	v_exp_f32_e32 v232, v70
	v_max3_f32 v129, v129, v56, v57
	v_exp_f32_e32 v233, v71
	v_max3_f32 v128, v128, v73, v74
	v_exp_f32_e32 v234, v72
	v_max3_f32 v129, v129, v58, v59
	v_exp_f32_e32 v235, v73
	v_max3_f32 v128, v128, v75, v76
	v_exp_f32_e32 v236, v74
	v_max3_f32 v129, v129, v60, v61
	v_exp_f32_e32 v237, v75
	v_max3_f32 v128, v128, v77, v78
	v_exp_f32_e32 v238, v76
	v_max3_f32 v129, v129, v62, v63
	v_exp_f32_e32 v239, v77
	v_max3_f32 v128, v128, v79, v48
	v_exp_f32_e32 v240, v78
	v_max_f32_e32 v128, v128, v129
	v_exp_f32_e32 v241, v79
	v_mov_b32_e32 v129, v128
	s_nop 1
	v_permlane32_swap_b32_e32 v128, v129
	v_max_f32_e32 v128, v128, v129
	v_cmp_ge_f32_e32 vcc, s83, v128
	v_mov_b32_e32 v161, 1.0
	s_cmp_eq_u64 vcc, exec
	s_cbranch_scc1 .Lsp_mo
	s_branch .LBB0_1245

; #define SBAR() __builtin_amdgcn_sched_barrier(0)
; #define PK4(P, BASE, OUT) do { u32x4 w = {cvtpk_a(P[BASE + 0], P[BASE + 1]), cvtpk_a(P[BASE + 2], P[BASE + 3]), cvtpk_a(P[BASE + 4], P[BASE + 5]), cvtpk_a(P[BASE + 6], P[BASE + 7])}; \
;     OUT = *reinterpret_cast<bf16x8*>(&w); } while (0)
; #define SWAIT() asm volatile("s_waitcnt vmcnt(3)" ::: "memory")
; __device__ __forceinline__ float exp_pack(f32x16& p0, f32x16& p1, bf16x8& pa0, bf16x8& pa1, bf16x8& pa2, bf16x8& pa3) {
; #pragma unroll
;     for (int r = 0; r < 16; ++r) p0[r] = __builtin_amdgcn_exp2f(p0[r]);
; #pragma unroll
;     for (int r = 0; r < 16; ++r) p1[r] = __builtin_amdgcn_exp2f(p1[r]);
;     SBAR(); asm volatile("s_nop 1" ::: "memory"); SBAR();
;     ...
;     PK4(p0, 0, pa0); PK4(p0, 8, pa1); PK4(p1, 0, pa2); PK4(p1, 8, pa3);
;     ...
;     float ps0 = p0[0], ps1 = p1[0];
; #pragma unroll
;     for (int r = 1; r < 16; ++r) { ps0 += p0[r]; ps1 += p1[r]; }
;     float ps = ps0 + ps1;
;     { auto rr = __builtin_amdgcn_permlane32_swap(__float_as_uint(ps), __float_as_uint(ps), false, false);
;       ps = __uint_as_float(rr[0]) + __uint_as_float(rr[1]); }
;     return ps;
; template <bool MLA>
; __device__ __forceinline__ void attn_core(const bf16_t* __restrict__ Qb, const bf16_t* __restrict__ Kh, const bf16_t* __restrict__ Vh, int seq, char* lds,
;                                           f32x16 (&o)[Cfg<MLA>::NCB], const int wid  , const int g  ) {
;     ...
;         SWAIT(); if (j + 3 < NT) SWRITE(((j + 3) % 3) * SHM_K, ((j + 3) & 3) * SHM_V, SO);
.Lsp_mo:
	v_exp_f32_e32 v48, v48
	v_cvt_pk_bf16_f32 v140, v226, v227
	v_cvt_pk_bf16_f32 v136, v234, v235
	v_exp_f32_e32 v49, v49
	v_add_f32_e32 v226, v226, v227
	v_exp_f32_e32 v50, v50
	v_add_f32_e32 v234, v234, v235
	v_add_f32_e32 v226, v228, v226
	v_exp_f32_e32 v51, v51
	v_add_f32_e32 v234, v236, v234
	v_exp_f32_e32 v52, v52
	v_cvt_pk_bf16_f32 v141, v228, v229
	v_add_f32_e32 v226, v229, v226
	v_exp_f32_e32 v53, v53
	v_add_f32_e32 v234, v237, v234
	v_exp_f32_e32 v54, v54
	v_cvt_pk_bf16_f32 v137, v236, v237
	v_add_f32_e32 v226, v230, v226
	v_exp_f32_e32 v55, v55
	v_add_f32_e32 v234, v238, v234
	v_exp_f32_e32 v56, v56
	v_cvt_pk_bf16_f32 v142, v230, v231
	v_add_f32_e32 v226, v231, v226
	v_exp_f32_e32 v57, v57
	v_add_f32_e32 v234, v239, v234
	v_exp_f32_e32 v58, v58
	v_cvt_pk_bf16_f32 v138, v238, v239
	v_add_f32_e32 v226, v232, v226
	v_exp_f32_e32 v59, v59
	v_add_f32_e32 v234, v240, v234
	v_exp_f32_e32 v60, v60
	v_cvt_pk_bf16_f32 v143, v232, v233
	v_add_f32_e32 v226, v233, v226
	v_exp_f32_e32 v61, v61
	v_add_f32_e32 v234, v241, v234
	v_exp_f32_e32 v62, v62
	v_cvt_pk_bf16_f32 v139, v240, v241
	v_add_f32_e32 v226, v226, v234
	v_exp_f32_e32 v63, v63
	v_cvt_pk_bf16_f32 v132, v48, v49
	v_cvt_pk_bf16_f32 v128, v56, v57
	v_add_f32_e32 v48, v48, v49
	v_add_f32_e32 v56, v56, v57
	v_add_f32_e32 v48, v50, v48
	v_add_f32_e32 v56, v58, v56
	v_cvt_pk_bf16_f32 v133, v50, v51
	v_add_f32_e32 v48, v51, v48
	v_add_f32_e32 v56, v59, v56
	v_cvt_pk_bf16_f32 v129, v58, v59
	v_add_f32_e32 v48, v52, v48
	v_add_f32_e32 v56, v60, v56
	v_cvt_pk_bf16_f32 v134, v52, v53
	v_add_f32_e32 v48, v53, v48
	v_add_f32_e32 v56, v61, v56
	v_cvt_pk_bf16_f32 v130, v60, v61
	v_add_f32_e32 v48, v54, v48
	v_add_f32_e32 v56, v62, v56
	v_cvt_pk_bf16_f32 v135, v54, v55
	v_add_f32_e32 v48, v55, v48
	v_add_f32_e32 v56, v63, v56
	v_cvt_pk_bf16_f32 v131, v62, v63
	v_add_f32_e32 v48, v48, v56
	v_add_f32_e32 v48, v48, v226
	s_waitcnt vmcnt(3)
	s_cmpk_gt_u32 s61, 0x80
	s_cbranch_scc1 .LBB0_1227
	s_mul_i32 s10, s51, 0xab
	s_bfe_u32 s10, s10, 0x70009
	s_mul_i32 s10, s10, 3
	s_sub_i32 s10, s51, s10
	s_and_b32 s10, s10, 0xff
	s_mulk_i32 s10, 0x4400
	v_add_u32_e32 v50, s62, v145
	s_add_i32 s16, s10, 0
	s_waitcnt vmcnt(5)
	ds_write_b128 v50, v[116:119]
	v_add_u32_e32 v50, s16, v144
	s_and_b64 vcc, exec, s[4:5]
	s_waitcnt vmcnt(4)
	ds_write_b128 v50, v[124:127] offset:32768
	s_cbranch_vccnz .LBB0_1227
	v_add_u32_e32 v50, s16, v150
	s_waitcnt vmcnt(3)
	ds_write_b128 v50, v[120:123] offset:32768
	s_branch .LBB0_1227
